# GEMM: first K-loop iteration peeled, first MFMA per accumulator takes C=0, per-tile accumulator zeroing (255 v_mov) removed
# speedup vs baseline: 1.0103x; 1.0071x over previous
.LBB0_374:
	s_andn2_b64 vcc, exec, s[38:39]
	s_cbranch_vccz .Lk_go
	v_mov_b32_e32 v127, 0
	v_mov_b32_e32 v126, v127
	v_mov_b32_e32 v125, v127
	v_mov_b32_e32 v124, v127
	v_mov_b32_e32 v131, v127
	v_mov_b32_e32 v130, v127
	v_mov_b32_e32 v129, v127
	v_mov_b32_e32 v128, v127
	v_mov_b32_e32 v111, v127
	v_mov_b32_e32 v110, v127
	v_mov_b32_e32 v109, v127
	v_mov_b32_e32 v108, v127
	v_mov_b32_e32 v115, v127
	v_mov_b32_e32 v114, v127
	v_mov_b32_e32 v113, v127
	v_mov_b32_e32 v112, v127
	v_mov_b32_e32 v95, v127
	v_mov_b32_e32 v94, v127
	v_mov_b32_e32 v93, v127
	v_mov_b32_e32 v92, v127
	v_mov_b32_e32 v99, v127
	v_mov_b32_e32 v98, v127
	v_mov_b32_e32 v97, v127
	v_mov_b32_e32 v96, v127
	v_mov_b32_e32 v79, v127
	v_mov_b32_e32 v78, v127
	v_mov_b32_e32 v77, v127
	v_mov_b32_e32 v76, v127
	v_mov_b32_e32 v83, v127
	v_mov_b32_e32 v82, v127
	v_mov_b32_e32 v81, v127
	v_mov_b32_e32 v80, v127
	v_mov_b32_e32 v119, v127
	v_mov_b32_e32 v118, v127
	v_mov_b32_e32 v117, v127
	v_mov_b32_e32 v116, v127
	v_mov_b32_e32 v123, v127
	v_mov_b32_e32 v122, v127
	v_mov_b32_e32 v121, v127
	v_mov_b32_e32 v120, v127
	v_mov_b32_e32 v103, v127
	v_mov_b32_e32 v102, v127
	v_mov_b32_e32 v101, v127
	v_mov_b32_e32 v100, v127
	v_mov_b32_e32 v107, v127
	v_mov_b32_e32 v106, v127
	v_mov_b32_e32 v105, v127
	v_mov_b32_e32 v104, v127
	v_mov_b32_e32 v87, v127
	v_mov_b32_e32 v86, v127
	v_mov_b32_e32 v85, v127
	v_mov_b32_e32 v84, v127
	v_mov_b32_e32 v91, v127
	v_mov_b32_e32 v90, v127
	v_mov_b32_e32 v89, v127
	v_mov_b32_e32 v88, v127
	v_mov_b32_e32 v71, v127
	v_mov_b32_e32 v70, v127
	v_mov_b32_e32 v69, v127
	v_mov_b32_e32 v68, v127
	v_mov_b32_e32 v75, v127
	v_mov_b32_e32 v74, v127
	v_mov_b32_e32 v73, v127
	v_mov_b32_e32 v72, v127
	v_mov_b32_e32 v63, v127
	v_mov_b32_e32 v62, v127
	v_mov_b32_e32 v61, v127
	v_mov_b32_e32 v60, v127
	v_mov_b32_e32 v67, v127
	v_mov_b32_e32 v66, v127
	v_mov_b32_e32 v65, v127
	v_mov_b32_e32 v64, v127
	v_mov_b32_e32 v47, v127
	v_mov_b32_e32 v46, v127
	v_mov_b32_e32 v45, v127
	v_mov_b32_e32 v44, v127
	v_mov_b32_e32 v51, v127
	v_mov_b32_e32 v50, v127
	v_mov_b32_e32 v49, v127
	v_mov_b32_e32 v48, v127
	v_mov_b32_e32 v31, v127
	v_mov_b32_e32 v30, v127
	v_mov_b32_e32 v29, v127
	v_mov_b32_e32 v28, v127
	v_mov_b32_e32 v35, v127
	v_mov_b32_e32 v34, v127
	v_mov_b32_e32 v33, v127
	v_mov_b32_e32 v32, v127
	v_mov_b32_e32 v15, v127
	v_mov_b32_e32 v14, v127
	v_mov_b32_e32 v13, v127
	v_mov_b32_e32 v12, v127
	v_mov_b32_e32 v19, v127
	v_mov_b32_e32 v18, v127
	v_mov_b32_e32 v17, v127
	v_mov_b32_e32 v16, v127
	v_mov_b32_e32 v55, v127
	v_mov_b32_e32 v54, v127
	v_mov_b32_e32 v53, v127
	v_mov_b32_e32 v52, v127
	v_mov_b32_e32 v59, v127
	v_mov_b32_e32 v58, v127
	v_mov_b32_e32 v57, v127
	v_mov_b32_e32 v56, v127
	v_mov_b32_e32 v39, v127
	v_mov_b32_e32 v38, v127
	v_mov_b32_e32 v37, v127
	v_mov_b32_e32 v36, v127
	v_mov_b32_e32 v43, v127
	v_mov_b32_e32 v42, v127
	v_mov_b32_e32 v41, v127
	v_mov_b32_e32 v40, v127
	v_mov_b32_e32 v23, v127
	v_mov_b32_e32 v22, v127
	v_mov_b32_e32 v21, v127
	v_mov_b32_e32 v20, v127
	v_mov_b32_e32 v27, v127
	v_mov_b32_e32 v26, v127
	v_mov_b32_e32 v25, v127
	v_mov_b32_e32 v24, v127
	v_mov_b32_e32 v11, v127
	v_mov_b32_e32 v10, v127
	v_mov_b32_e32 v9, v127
	v_mov_b32_e32 v8, v127
	v_mov_b32_e32 v7, v127
	v_mov_b32_e32 v6, v127
	v_mov_b32_e32 v5, v127
	v_mov_b32_e32 v4, v127
	s_branch .LBB0_377
.Lk_go:
	s_add_u32 s4, s4, 0x80
	s_addc_u32 s5, s5, 0
	s_add_u32 s1, s10, 0x100
	s_addc_u32 vcc_lo, s11, 0
	s_mov_b32 s10, 0
	s_add_i32 vcc_hi, s10, 2
	s_add_u32 s56, s4, 0x80
	s_addc_u32 s11, s5, 0
	s_add_i32 s98, 0, 0x10000
	v_add_u32_e32 v1, s98, v238
	ds_read_b128 v[132:135], v1
	ds_read_b128 v[136:139], v1 offset:1024
	ds_read_b128 v[140:143], v1 offset:2048
	ds_read_b128 v[144:147], v1 offset:3072
	s_cmp_eq_u32 s75, s10
	s_cselect_b32 s10, s50, s56
	s_cselect_b32 s11, s51, s11
	s_cselect_b32 s57, s97, vcc_lo
	s_cselect_b32 s56, s96, s1
	v_lshl_add_u64 v[180:181], s[4:5], 0, v[206:207]
	s_add_i32 m0, s73, 0xc000
	ds_read_b128 v[148:151], v240
	ds_read_b128 v[152:155], v240 offset:1024
	ds_read_b128 v[156:159], v240 offset:2048
	ds_read_b128 v[160:163], v240 offset:3072
	ds_read_b128 v[164:167], v240 offset:4096
	ds_read_b128 v[168:171], v240 offset:5120
	ds_read_b128 v[172:175], v240 offset:6144
	ds_read_b128 v[176:179], v240 offset:7168
	global_load_lds_dwordx4 v[180:181], off
	v_lshl_add_u64 v[180:181], s[4:5], 0, v[208:209]
	s_add_i32 m0, s73, 0xe000
	s_nop 0
	global_load_lds_dwordx4 v[180:181], off
	s_waitcnt lgkmcnt(8)
	s_waitcnt vmcnt(10)
	s_barrier
	s_waitcnt lgkmcnt(0)
	s_setprio 1
	s_waitcnt lgkmcnt(0)
	v_mfma_f32_16x16x32_f16 v[124:127], v[132:135], v[148:151], 0
	v_mfma_f32_16x16x32_f16 v[128:131], v[140:143], v[148:151], 0
	v_mfma_f32_16x16x32_f16 v[108:111], v[132:135], v[156:159], 0
	v_mfma_f32_16x16x32_f16 v[112:115], v[140:143], v[156:159], 0
	v_mfma_f32_16x16x32_f16 v[92:95], v[132:135], v[164:167], 0
	v_mfma_f32_16x16x32_f16 v[96:99], v[140:143], v[164:167], 0
	v_mfma_f32_16x16x32_f16 v[76:79], v[132:135], v[172:175], 0
	v_mfma_f32_16x16x32_f16 v[80:83], v[140:143], v[172:175], 0
	v_mfma_f32_16x16x32_f16 v[124:127], v[136:139], v[152:155], v[124:127]
	v_mfma_f32_16x16x32_f16 v[128:131], v[144:147], v[152:155], v[128:131]
	v_mfma_f32_16x16x32_f16 v[108:111], v[136:139], v[160:163], v[108:111]
	v_mfma_f32_16x16x32_f16 v[112:115], v[144:147], v[160:163], v[112:115]
	v_mfma_f32_16x16x32_f16 v[92:95], v[136:139], v[168:171], v[92:95]
	v_mfma_f32_16x16x32_f16 v[96:99], v[144:147], v[168:171], v[96:99]
	v_mfma_f32_16x16x32_f16 v[76:79], v[136:139], v[176:179], v[76:79]
	v_mfma_f32_16x16x32_f16 v[80:83], v[144:147], v[176:179], v[80:83]
	s_setprio 0
	s_barrier
	s_add_i32 s98, s98, s72
	v_add_u32_e32 v1, s58, v238
	v_lshl_add_u64 v[210:211], s[56:57], 0, v[200:201]
	s_mov_b32 m0, s98
	ds_read_b128 v[180:183], v1
	ds_read_b128 v[184:187], v1 offset:1024
	ds_read_b128 v[188:191], v1 offset:2048
	ds_read_b128 v[192:195], v1 offset:3072
	global_load_lds_dwordx4 v[210:211], off
	v_lshl_add_u64 v[212:213], s[56:57], 0, v[202:203]
	s_add_i32 m0, s98, 0x2000
	s_nop 0
	global_load_lds_dwordx4 v[212:213], off
	s_waitcnt vmcnt(10)
	s_barrier
	s_waitcnt lgkmcnt(0)
	s_setprio 1
	s_waitcnt lgkmcnt(0)
	v_mfma_f32_16x16x32_f16 v[116:119], v[180:183], v[148:151], 0
	v_mfma_f32_16x16x32_f16 v[120:123], v[188:191], v[148:151], 0
	v_mfma_f32_16x16x32_f16 v[100:103], v[180:183], v[156:159], 0
	v_mfma_f32_16x16x32_f16 v[104:107], v[188:191], v[156:159], 0
	v_mfma_f32_16x16x32_f16 v[84:87], v[180:183], v[164:167], 0
	v_mfma_f32_16x16x32_f16 v[88:91], v[188:191], v[164:167], 0
	v_mfma_f32_16x16x32_f16 v[68:71], v[180:183], v[172:175], 0
	v_mfma_f32_16x16x32_f16 v[72:75], v[188:191], v[172:175], 0
	v_mfma_f32_16x16x32_f16 v[116:119], v[184:187], v[152:155], v[116:119]
	v_mfma_f32_16x16x32_f16 v[120:123], v[192:195], v[152:155], v[120:123]
	v_mfma_f32_16x16x32_f16 v[100:103], v[184:187], v[160:163], v[100:103]
	v_mfma_f32_16x16x32_f16 v[104:107], v[192:195], v[160:163], v[104:107]
	v_mfma_f32_16x16x32_f16 v[84:87], v[184:187], v[168:171], v[84:87]
	v_mfma_f32_16x16x32_f16 v[88:91], v[192:195], v[168:171], v[88:91]
	v_mfma_f32_16x16x32_f16 v[68:71], v[184:187], v[176:179], v[68:71]
	v_mfma_f32_16x16x32_f16 v[72:75], v[192:195], v[176:179], v[72:75]
	s_setprio 0
	s_mov_b32 m0, s73
	v_lshl_add_u64 v[214:215], s[10:11], 0, v[200:201]
	s_barrier
	ds_read_b128 v[148:151], v240 offset:16384
	ds_read_b128 v[152:155], v240 offset:17408
	ds_read_b128 v[156:159], v240 offset:18432
	ds_read_b128 v[160:163], v240 offset:19456
	ds_read_b128 v[164:167], v240 offset:20480
	ds_read_b128 v[168:171], v240 offset:21504
	ds_read_b128 v[172:175], v240 offset:22528
	ds_read_b128 v[176:179], v240 offset:23552
	global_load_lds_dwordx4 v[214:215], off
	v_lshl_add_u64 v[216:217], s[10:11], 0, v[202:203]
	s_mov_b32 m0, s78
	s_nop 0
	global_load_lds_dwordx4 v[216:217], off
	s_barrier
	s_waitcnt lgkmcnt(0)
	s_setprio 1
	s_waitcnt lgkmcnt(0)
	v_mfma_f32_16x16x32_f16 v[60:63], v[132:135], v[148:151], 0
	v_mfma_f32_16x16x32_f16 v[64:67], v[140:143], v[148:151], 0
	v_mfma_f32_16x16x32_f16 v[44:47], v[132:135], v[156:159], 0
	v_mfma_f32_16x16x32_f16 v[48:51], v[140:143], v[156:159], 0
	v_mfma_f32_16x16x32_f16 v[28:31], v[132:135], v[164:167], 0
	v_mfma_f32_16x16x32_f16 v[32:35], v[140:143], v[164:167], 0
	v_mfma_f32_16x16x32_f16 v[12:15], v[132:135], v[172:175], 0
	v_mfma_f32_16x16x32_f16 v[16:19], v[140:143], v[172:175], 0
	v_mfma_f32_16x16x32_f16 v[60:63], v[136:139], v[152:155], v[60:63]
	v_mfma_f32_16x16x32_f16 v[64:67], v[144:147], v[152:155], v[64:67]
	v_mfma_f32_16x16x32_f16 v[44:47], v[136:139], v[160:163], v[44:47]
	v_mfma_f32_16x16x32_f16 v[48:51], v[144:147], v[160:163], v[48:51]
	v_mfma_f32_16x16x32_f16 v[28:31], v[136:139], v[168:171], v[28:31]
	v_mfma_f32_16x16x32_f16 v[32:35], v[144:147], v[168:171], v[32:35]
	v_mfma_f32_16x16x32_f16 v[12:15], v[136:139], v[176:179], v[12:15]
	v_mfma_f32_16x16x32_f16 v[16:19], v[144:147], v[176:179], v[16:19]
	s_setprio 0
	s_barrier
	s_add_u32 s56, s56, s28
	s_addc_u32 s57, s57, s29
	s_add_i32 s98, s58, s72
	v_lshl_add_u64 v[218:219], s[56:57], 0, v[200:201]
	s_mov_b32 m0, s98
	v_lshl_add_u64 v[220:221], s[56:57], 0, v[202:203]
	global_load_lds_dwordx4 v[218:219], off
	s_add_i32 m0, s98, 0x2000
	s_nop 0
	global_load_lds_dwordx4 v[220:221], off
	s_waitcnt vmcnt(10)
	s_barrier
	s_setprio 1
	v_mfma_f32_16x16x32_f16 v[52:55], v[180:183], v[148:151], 0
	v_mfma_f32_16x16x32_f16 v[56:59], v[188:191], v[148:151], 0
	v_mfma_f32_16x16x32_f16 v[36:39], v[180:183], v[156:159], 0
	v_mfma_f32_16x16x32_f16 v[40:43], v[188:191], v[156:159], 0
	v_mfma_f32_16x16x32_f16 v[20:23], v[180:183], v[164:167], 0
	v_mfma_f32_16x16x32_f16 v[24:27], v[188:191], v[164:167], 0
	v_mfma_f32_16x16x32_f16 v[8:11], v[180:183], v[172:175], 0
	v_mfma_f32_16x16x32_f16 v[4:7], v[188:191], v[172:175], 0
	v_mfma_f32_16x16x32_f16 v[52:55], v[184:187], v[152:155], v[52:55]
	v_mfma_f32_16x16x32_f16 v[56:59], v[192:195], v[152:155], v[56:59]
	v_mfma_f32_16x16x32_f16 v[36:39], v[184:187], v[160:163], v[36:39]
	v_mfma_f32_16x16x32_f16 v[40:43], v[192:195], v[160:163], v[40:43]
	v_mfma_f32_16x16x32_f16 v[20:23], v[184:187], v[168:171], v[20:23]
	v_mfma_f32_16x16x32_f16 v[24:27], v[192:195], v[168:171], v[24:27]
	v_mfma_f32_16x16x32_f16 v[8:11], v[184:187], v[176:179], v[8:11]
	v_mfma_f32_16x16x32_f16 v[4:7], v[192:195], v[176:179], v[4:7]
	s_setprio 0
	v_add_u32_e32 v1, s99, v238
	s_barrier
	ds_read_b128 v[132:135], v1
	ds_read_b128 v[136:139], v1 offset:1024
	ds_read_b128 v[140:143], v1 offset:2048
	ds_read_b128 v[144:147], v1 offset:3072
	s_add_u32 s10, s10, s28
	s_addc_u32 s11, s11, s29
	s_mov_b32 m0, s79
	v_lshl_add_u64 v[180:181], s[10:11], 0, v[200:201]
	ds_read_b128 v[148:151], v240 offset:32768
	ds_read_b128 v[152:155], v240 offset:33792
	ds_read_b128 v[156:159], v240 offset:34816
	ds_read_b128 v[160:163], v240 offset:35840
	ds_read_b128 v[164:167], v240 offset:36864
	ds_read_b128 v[168:171], v240 offset:37888
	ds_read_b128 v[172:175], v240 offset:38912
	ds_read_b128 v[176:179], v240 offset:39936
	global_load_lds_dwordx4 v[180:181], off
	v_lshl_add_u64 v[180:181], s[10:11], 0, v[202:203]
	s_mov_b32 m0, s60
	s_nop 0
	global_load_lds_dwordx4 v[180:181], off
	s_waitcnt lgkmcnt(8)
	s_waitcnt vmcnt(10)
	s_barrier
	s_waitcnt lgkmcnt(0)
	s_setprio 1
	s_waitcnt lgkmcnt(0)
	v_mfma_f32_16x16x32_f16 v[124:127], v[132:135], v[148:151], v[124:127]
	v_mfma_f32_16x16x32_f16 v[128:131], v[140:143], v[148:151], v[128:131]
	v_mfma_f32_16x16x32_f16 v[108:111], v[132:135], v[156:159], v[108:111]
	v_mfma_f32_16x16x32_f16 v[112:115], v[140:143], v[156:159], v[112:115]
	v_mfma_f32_16x16x32_f16 v[92:95], v[132:135], v[164:167], v[92:95]
	v_mfma_f32_16x16x32_f16 v[96:99], v[140:143], v[164:167], v[96:99]
	v_mfma_f32_16x16x32_f16 v[76:79], v[132:135], v[172:175], v[76:79]
	v_mfma_f32_16x16x32_f16 v[80:83], v[140:143], v[172:175], v[80:83]
	v_mfma_f32_16x16x32_f16 v[124:127], v[136:139], v[152:155], v[124:127]
	v_mfma_f32_16x16x32_f16 v[128:131], v[144:147], v[152:155], v[128:131]
	v_mfma_f32_16x16x32_f16 v[108:111], v[136:139], v[160:163], v[108:111]
	v_mfma_f32_16x16x32_f16 v[112:115], v[144:147], v[160:163], v[112:115]
	v_mfma_f32_16x16x32_f16 v[92:95], v[136:139], v[168:171], v[92:95]
	v_mfma_f32_16x16x32_f16 v[96:99], v[144:147], v[168:171], v[96:99]
	v_mfma_f32_16x16x32_f16 v[76:79], v[136:139], v[176:179], v[76:79]
	v_mfma_f32_16x16x32_f16 v[80:83], v[144:147], v[176:179], v[80:83]
	s_setprio 0
	s_barrier
	s_add_i32 s10, 0, 0x1c000
	s_add_i32 s11, s99, s72
	v_add_u32_e32 v1, s10, v238
	v_lshl_add_u64 v[210:211], v[210:211], 0, s[86:87]
	s_mov_b32 m0, s11
	ds_read_b128 v[180:183], v1
	ds_read_b128 v[184:187], v1 offset:1024
	ds_read_b128 v[188:191], v1 offset:2048
	ds_read_b128 v[192:195], v1 offset:3072
	global_load_lds_dwordx4 v[210:211], off
	v_lshl_add_u64 v[210:211], v[212:213], 0, s[86:87]
	s_add_i32 m0, s11, 0x2000
	s_nop 0
	global_load_lds_dwordx4 v[210:211], off
	s_waitcnt vmcnt(10)
	s_barrier
	s_waitcnt lgkmcnt(0)
	s_setprio 1
	s_waitcnt lgkmcnt(0)
	v_mfma_f32_16x16x32_f16 v[116:119], v[180:183], v[148:151], v[116:119]
	v_mfma_f32_16x16x32_f16 v[120:123], v[188:191], v[148:151], v[120:123]
	v_mfma_f32_16x16x32_f16 v[100:103], v[180:183], v[156:159], v[100:103]
	v_mfma_f32_16x16x32_f16 v[104:107], v[188:191], v[156:159], v[104:107]
	v_mfma_f32_16x16x32_f16 v[84:87], v[180:183], v[164:167], v[84:87]
	v_mfma_f32_16x16x32_f16 v[88:91], v[188:191], v[164:167], v[88:91]
	v_mfma_f32_16x16x32_f16 v[68:71], v[180:183], v[172:175], v[68:71]
	v_mfma_f32_16x16x32_f16 v[72:75], v[188:191], v[172:175], v[72:75]
	v_mfma_f32_16x16x32_f16 v[116:119], v[184:187], v[152:155], v[116:119]
	v_mfma_f32_16x16x32_f16 v[120:123], v[192:195], v[152:155], v[120:123]
	v_mfma_f32_16x16x32_f16 v[100:103], v[184:187], v[160:163], v[100:103]
	v_mfma_f32_16x16x32_f16 v[104:107], v[192:195], v[160:163], v[104:107]
	v_mfma_f32_16x16x32_f16 v[84:87], v[184:187], v[168:171], v[84:87]
	v_mfma_f32_16x16x32_f16 v[88:91], v[192:195], v[168:171], v[88:91]
	v_mfma_f32_16x16x32_f16 v[68:71], v[184:187], v[176:179], v[68:71]
	v_mfma_f32_16x16x32_f16 v[72:75], v[192:195], v[176:179], v[72:75]
	s_setprio 0
	s_mov_b32 m0, s77
	v_lshl_add_u64 v[210:211], v[214:215], 0, s[86:87]
	s_barrier
	ds_read_b128 v[148:151], v240 offset:49152
	ds_read_b128 v[152:155], v240 offset:50176
	ds_read_b128 v[156:159], v240 offset:51200
	ds_read_b128 v[160:163], v240 offset:52224
	ds_read_b128 v[164:167], v240 offset:53248
	ds_read_b128 v[168:171], v240 offset:54272
	ds_read_b128 v[172:175], v240 offset:55296
	ds_read_b128 v[176:179], v240 offset:56320
	global_load_lds_dwordx4 v[210:211], off
	v_lshl_add_u64 v[210:211], v[216:217], 0, s[86:87]
	s_mov_b32 m0, s64
	s_nop 0
	global_load_lds_dwordx4 v[210:211], off
	s_barrier
	s_waitcnt lgkmcnt(0)
	s_setprio 1
	s_waitcnt lgkmcnt(0)
	v_mfma_f32_16x16x32_f16 v[60:63], v[132:135], v[148:151], v[60:63]
	v_mfma_f32_16x16x32_f16 v[64:67], v[140:143], v[148:151], v[64:67]
	v_mfma_f32_16x16x32_f16 v[44:47], v[132:135], v[156:159], v[44:47]
	v_mfma_f32_16x16x32_f16 v[48:51], v[140:143], v[156:159], v[48:51]
	v_mfma_f32_16x16x32_f16 v[28:31], v[132:135], v[164:167], v[28:31]
	v_mfma_f32_16x16x32_f16 v[32:35], v[140:143], v[164:167], v[32:35]
	v_mfma_f32_16x16x32_f16 v[12:15], v[132:135], v[172:175], v[12:15]
	v_mfma_f32_16x16x32_f16 v[16:19], v[140:143], v[172:175], v[16:19]
	v_mfma_f32_16x16x32_f16 v[60:63], v[136:139], v[152:155], v[60:63]
	v_mfma_f32_16x16x32_f16 v[64:67], v[144:147], v[152:155], v[64:67]
	v_mfma_f32_16x16x32_f16 v[44:47], v[136:139], v[160:163], v[44:47]
	v_mfma_f32_16x16x32_f16 v[48:51], v[144:147], v[160:163], v[48:51]
	v_mfma_f32_16x16x32_f16 v[28:31], v[136:139], v[168:171], v[28:31]
	v_mfma_f32_16x16x32_f16 v[32:35], v[144:147], v[168:171], v[32:35]
	v_mfma_f32_16x16x32_f16 v[12:15], v[136:139], v[176:179], v[12:15]
	v_mfma_f32_16x16x32_f16 v[16:19], v[144:147], v[176:179], v[16:19]
	s_setprio 0
	s_barrier
	s_add_i32 s10, s10, s72
	v_lshl_add_u64 v[132:133], v[218:219], 0, s[86:87]
	s_mov_b32 m0, s10
	s_nop 0
	global_load_lds_dwordx4 v[132:133], off
	v_lshl_add_u64 v[132:133], v[220:221], 0, s[86:87]
	s_add_i32 m0, s10, 0x2000
	s_nop 0
	global_load_lds_dwordx4 v[132:133], off
	s_waitcnt vmcnt(10)
	s_barrier
	s_setprio 1
	v_mfma_f32_16x16x32_f16 v[52:55], v[180:183], v[148:151], v[52:55]
	v_mfma_f32_16x16x32_f16 v[56:59], v[188:191], v[148:151], v[56:59]
	v_mfma_f32_16x16x32_f16 v[36:39], v[180:183], v[156:159], v[36:39]
	v_mfma_f32_16x16x32_f16 v[40:43], v[188:191], v[156:159], v[40:43]
	v_mfma_f32_16x16x32_f16 v[20:23], v[180:183], v[164:167], v[20:23]
	v_mfma_f32_16x16x32_f16 v[24:27], v[188:191], v[164:167], v[24:27]
	v_mfma_f32_16x16x32_f16 v[8:11], v[180:183], v[172:175], v[8:11]
	v_mfma_f32_16x16x32_f16 v[4:7], v[188:191], v[172:175], v[4:7]
	v_mfma_f32_16x16x32_f16 v[52:55], v[184:187], v[152:155], v[52:55]
	v_mfma_f32_16x16x32_f16 v[56:59], v[192:195], v[152:155], v[56:59]
	v_mfma_f32_16x16x32_f16 v[36:39], v[184:187], v[160:163], v[36:39]
	v_mfma_f32_16x16x32_f16 v[40:43], v[192:195], v[160:163], v[40:43]
	v_mfma_f32_16x16x32_f16 v[20:23], v[184:187], v[168:171], v[20:23]
	v_mfma_f32_16x16x32_f16 v[24:27], v[192:195], v[168:171], v[24:27]
	v_mfma_f32_16x16x32_f16 v[8:11], v[184:187], v[176:179], v[8:11]
	v_mfma_f32_16x16x32_f16 v[4:7], v[192:195], v[176:179], v[4:7]
	s_setprio 0
	s_add_u32 s4, s4, 0x100
	s_addc_u32 s5, s5, 0
	s_add_u32 s1, s1, 0x100
	s_addc_u32 vcc_lo, vcc_lo, 0
	s_cmp_ge_i32 vcc_hi, s67
	s_mov_b32 s10, vcc_hi
	s_barrier
	s_cbranch_scc1 .LBB0_377
